# flash loops: lane^32 max exchange via v_permlane32_swap instead of ds_bpermute; diff loop row-sum without v_mov/pk_add shuffles
# speedup vs baseline: 1.0140x; 1.0005x over previous
.LBB0_1566:
	s_nop 7
	v_max_f32_e32 v116, v65, v65
	v_max_f32_e32 v117, v64, v64
	v_max_f32_e32 v116, v117, v116
	v_max3_f32 v117, v66, v67, v49
	v_max3_f32 v116, v116, v48, v50
	v_max3_f32 v116, v116, v51, v68
	v_max3_f32 v117, v117, v70, v71
	v_max3_f32 v116, v116, v69, v52
	v_max3_f32 v117, v117, v54, v55
	v_max3_f32 v116, v116, v53, v72
	v_max3_f32 v117, v117, v74, v75
	v_max3_f32 v116, v116, v73, v56
	v_max3_f32 v117, v117, v58, v59
	v_max3_f32 v116, v116, v57, v76
	v_max3_f32 v117, v117, v78, v79
	v_add_u32_e32 v10, s11, v110
	v_max3_f32 v116, v116, v77, v60
	v_max3_f32 v117, v117, v62, v63
	v_add_u32_e32 v115, v10, v111
	v_max3_f32 v116, v116, v61, v117
	ds_read_b64_tr_b16 v[88:89], v115 offset:18432
	ds_read_b64_tr_b16 v[90:91], v115 offset:19584
	ds_read_b64_tr_b16 v[86:87], v115 offset:19648
	ds_read_b64_tr_b16 v[84:85], v115 offset:18496
	ds_read_b64_tr_b16 v[80:81], v115 offset:20736
	ds_read_b64_tr_b16 v[82:83], v115 offset:21888
	ds_read_b64_tr_b16 v[12:13], v115 offset:21952
	ds_read_b64_tr_b16 v[10:11], v115 offset:20800
	v_mov_b32_e32 v117, v116
	s_nop 1
	v_permlane32_swap_b32_e32 v117, v116
	s_waitcnt lgkmcnt(0)
	v_max_f32_e32 v116, v116, v117
	v_cmp_lt_f32_e32 vcc, s28, v116
	s_cbranch_vccz .LBB0_1561
	v_max_f32_e32 v116, v116, v116
	v_max_f32_e32 v117, 0, v116
	v_exp_f32_e64 v116, -v117
	v_add_f32_e32 v93, v93, v117
	v_sub_f32_e32 v79, v79, v117
	v_sub_f32_e32 v78, v78, v117
	v_mul_f32_e32 v15, v15, v116
	v_sub_f32_e32 v77, v77, v117
	v_sub_f32_e32 v76, v76, v117
	v_sub_f32_e32 v75, v75, v117
	v_sub_f32_e32 v74, v74, v117
	v_sub_f32_e32 v73, v73, v117
	v_sub_f32_e32 v72, v72, v117
	v_sub_f32_e32 v71, v71, v117
	v_sub_f32_e32 v70, v70, v117
	v_sub_f32_e32 v69, v69, v117
	v_sub_f32_e32 v68, v68, v117
	v_sub_f32_e32 v67, v67, v117
	v_sub_f32_e32 v66, v66, v117
	v_sub_f32_e32 v65, v65, v117
	v_sub_f32_e32 v64, v64, v117
	v_sub_f32_e32 v63, v63, v117
	v_sub_f32_e32 v62, v62, v117
	v_sub_f32_e32 v61, v61, v117
	v_sub_f32_e32 v60, v60, v117
	v_sub_f32_e32 v59, v59, v117
	v_sub_f32_e32 v58, v58, v117
	v_sub_f32_e32 v57, v57, v117
	v_sub_f32_e32 v56, v56, v117
	v_sub_f32_e32 v55, v55, v117
	v_sub_f32_e32 v54, v54, v117
	v_sub_f32_e32 v53, v53, v117
	v_sub_f32_e32 v52, v52, v117
	v_sub_f32_e32 v51, v51, v117
	v_sub_f32_e32 v50, v50, v117
	v_sub_f32_e32 v49, v49, v117
	v_sub_f32_e32 v48, v48, v117
	v_pk_mul_f32 v[46:47], v[46:47], v[116:117] op_sel_hi:[1,0]
	v_pk_mul_f32 v[44:45], v[44:45], v[116:117] op_sel_hi:[1,0]
	v_pk_mul_f32 v[42:43], v[42:43], v[116:117] op_sel_hi:[1,0]
	v_pk_mul_f32 v[40:41], v[40:41], v[116:117] op_sel_hi:[1,0]
	v_pk_mul_f32 v[38:39], v[38:39], v[116:117] op_sel_hi:[1,0]
	v_pk_mul_f32 v[36:37], v[36:37], v[116:117] op_sel_hi:[1,0]
	v_pk_mul_f32 v[34:35], v[34:35], v[116:117] op_sel_hi:[1,0]
	v_pk_mul_f32 v[32:33], v[32:33], v[116:117] op_sel_hi:[1,0]
	v_pk_mul_f32 v[30:31], v[30:31], v[116:117] op_sel_hi:[1,0]
	v_pk_mul_f32 v[28:29], v[28:29], v[116:117] op_sel_hi:[1,0]
	v_pk_mul_f32 v[26:27], v[26:27], v[116:117] op_sel_hi:[1,0]
	v_pk_mul_f32 v[24:25], v[24:25], v[116:117] op_sel_hi:[1,0]
	v_pk_mul_f32 v[22:23], v[22:23], v[116:117] op_sel_hi:[1,0]
	v_pk_mul_f32 v[20:21], v[20:21], v[116:117] op_sel_hi:[1,0]
	v_pk_mul_f32 v[18:19], v[18:19], v[116:117] op_sel_hi:[1,0]
	v_pk_mul_f32 v[16:17], v[16:17], v[116:117] op_sel_hi:[1,0]
	s_branch .LBB0_1561

.LBB0_1657:
	s_nop 7
	v_max_f32_e32 v132, v97, v97
	v_max_f32_e32 v133, v96, v96
	v_max_f32_e32 v132, v133, v132
	v_max3_f32 v133, v98, v99, v81
	v_max3_f32 v132, v132, v80, v82
	v_max3_f32 v132, v132, v83, v100
	v_max3_f32 v133, v133, v102, v103
	v_max3_f32 v132, v132, v101, v84
	v_max3_f32 v133, v133, v86, v87
	v_max3_f32 v132, v132, v85, v104
	v_max3_f32 v133, v133, v106, v107
	v_max3_f32 v132, v132, v105, v88
	v_max3_f32 v133, v133, v90, v91
	v_max3_f32 v132, v132, v89, v108
	v_max3_f32 v133, v133, v110, v111
	v_add_u32_e32 v10, s81, v128
	v_max3_f32 v132, v132, v109, v92
	v_max3_f32 v133, v133, v94, v95
	v_add_u32_e32 v131, v10, v129
	v_max3_f32 v132, v132, v93, v133
	ds_read_b64_tr_b16 v[120:121], v131 offset:18432
	ds_read_b64_tr_b16 v[122:123], v131 offset:19584
	ds_read_b64_tr_b16 v[118:119], v131 offset:19648
	ds_read_b64_tr_b16 v[116:117], v131 offset:18496
	ds_read_b64_tr_b16 v[112:113], v131 offset:20736
	ds_read_b64_tr_b16 v[114:115], v131 offset:21888
	ds_read_b64_tr_b16 v[12:13], v131 offset:21952
	ds_read_b64_tr_b16 v[10:11], v131 offset:20800
	v_mov_b32_e32 v133, v132
	s_nop 1
	v_permlane32_swap_b32_e32 v133, v132
	s_waitcnt lgkmcnt(0)
	v_max_f32_e32 v132, v132, v133
	v_cmp_lt_f32_e32 vcc, s82, v132
	s_cbranch_vccz .LBB0_1650
	v_max_f32_e32 v132, v132, v132
	v_max_f32_e32 v133, 0, v132
	v_exp_f32_e64 v132, -v133
	v_add_f32_e32 v130, v130, v133
	v_sub_f32_e32 v111, v111, v133
	v_sub_f32_e32 v110, v110, v133
	v_mul_f32_e32 v194, v194, v132
	v_sub_f32_e32 v109, v109, v133
	v_sub_f32_e32 v108, v108, v133
	v_sub_f32_e32 v107, v107, v133
	v_sub_f32_e32 v106, v106, v133
	v_sub_f32_e32 v105, v105, v133
	v_sub_f32_e32 v104, v104, v133
	v_sub_f32_e32 v103, v103, v133
	v_sub_f32_e32 v102, v102, v133
	v_sub_f32_e32 v101, v101, v133
	v_sub_f32_e32 v100, v100, v133
	v_sub_f32_e32 v99, v99, v133
	v_sub_f32_e32 v98, v98, v133
	v_sub_f32_e32 v97, v97, v133
	v_sub_f32_e32 v96, v96, v133
	v_sub_f32_e32 v95, v95, v133
	v_sub_f32_e32 v94, v94, v133
	v_sub_f32_e32 v93, v93, v133
	v_sub_f32_e32 v92, v92, v133
	v_sub_f32_e32 v91, v91, v133
	v_sub_f32_e32 v90, v90, v133
	v_sub_f32_e32 v89, v89, v133
	v_sub_f32_e32 v88, v88, v133
	v_sub_f32_e32 v87, v87, v133
	v_sub_f32_e32 v86, v86, v133
	v_sub_f32_e32 v85, v85, v133
	v_sub_f32_e32 v84, v84, v133
	v_sub_f32_e32 v83, v83, v133
	v_sub_f32_e32 v82, v82, v133
	v_sub_f32_e32 v81, v81, v133
	v_sub_f32_e32 v80, v80, v133
	v_pk_mul_f32 v[78:79], v[78:79], v[132:133] op_sel_hi:[1,0]
	v_pk_mul_f32 v[76:77], v[76:77], v[132:133] op_sel_hi:[1,0]
	v_pk_mul_f32 v[74:75], v[74:75], v[132:133] op_sel_hi:[1,0]
	v_pk_mul_f32 v[72:73], v[72:73], v[132:133] op_sel_hi:[1,0]
	v_pk_mul_f32 v[70:71], v[70:71], v[132:133] op_sel_hi:[1,0]
	v_pk_mul_f32 v[68:69], v[68:69], v[132:133] op_sel_hi:[1,0]
	v_pk_mul_f32 v[66:67], v[66:67], v[132:133] op_sel_hi:[1,0]
	v_pk_mul_f32 v[64:65], v[64:65], v[132:133] op_sel_hi:[1,0]
	v_pk_mul_f32 v[62:63], v[62:63], v[132:133] op_sel_hi:[1,0]
	v_pk_mul_f32 v[60:61], v[60:61], v[132:133] op_sel_hi:[1,0]
	v_pk_mul_f32 v[58:59], v[58:59], v[132:133] op_sel_hi:[1,0]
	v_pk_mul_f32 v[56:57], v[56:57], v[132:133] op_sel_hi:[1,0]
	v_pk_mul_f32 v[54:55], v[54:55], v[132:133] op_sel_hi:[1,0]
	v_pk_mul_f32 v[52:53], v[52:53], v[132:133] op_sel_hi:[1,0]
	v_pk_mul_f32 v[50:51], v[50:51], v[132:133] op_sel_hi:[1,0]
	v_pk_mul_f32 v[48:49], v[48:49], v[132:133] op_sel_hi:[1,0]
	s_branch .LBB0_1650

.LBB0_1668:
	s_nop 8
	v_max_f32_e32 v176, v129, v129
	v_max_f32_e32 v177, v128, v128
	v_max_f32_e32 v176, v177, v176
	v_max3_f32 v177, v130, v131, v113
	v_max3_f32 v176, v176, v112, v114
	v_max3_f32 v176, v176, v115, v132
	v_max3_f32 v177, v177, v134, v135
	v_max3_f32 v176, v176, v133, v116
	v_max3_f32 v177, v177, v118, v119
	v_max3_f32 v176, v176, v117, v136
	v_max3_f32 v177, v177, v138, v139
	v_max3_f32 v176, v176, v137, v120
	v_max3_f32 v177, v177, v122, v123
	v_max3_f32 v176, v176, v121, v140
	v_max3_f32 v177, v177, v142, v143
	v_add_u32_e32 v10, s5, v201
	v_max3_f32 v176, v176, v141, v124
	v_max3_f32 v177, v177, v126, v127
	v_add_u32_e32 v205, v10, v202
	v_max3_f32 v176, v176, v125, v177
	ds_read_b64_tr_b16 v[168:169], v205 offset:18432
	ds_read_b64_tr_b16 v[170:171], v205 offset:19584
	ds_read_b64_tr_b16 v[166:167], v205 offset:19648
	ds_read_b64_tr_b16 v[164:165], v205 offset:18496
	ds_read_b64_tr_b16 v[160:161], v205 offset:20736
	ds_read_b64_tr_b16 v[162:163], v205 offset:21888
	ds_read_b64_tr_b16 v[12:13], v205 offset:21952
	ds_read_b64_tr_b16 v[10:11], v205 offset:20800
	v_mov_b32_e32 v177, v176
	v_mov_b32_e32 v206, v176
	s_nop 1
	v_permlane32_swap_b32_e32 v177, v206
	s_waitcnt lgkmcnt(0)
	v_max_f32_e32 v206, v206, v177
	v_cmp_lt_f32_e32 vcc, s28, v206
	s_cbranch_vccz .LBB0_1663
	v_max_f32_e32 v176, v206, v206
	v_max_f32_e32 v177, 0, v176
	v_exp_f32_e64 v176, -v177
	v_add_f32_e32 v204, v204, v177
	v_sub_f32_e32 v143, v143, v177
	v_sub_f32_e32 v142, v142, v177
	v_mul_f32_e32 v196, v196, v176
	v_sub_f32_e32 v141, v141, v177
	v_sub_f32_e32 v140, v140, v177
	v_sub_f32_e32 v139, v139, v177
	v_sub_f32_e32 v138, v138, v177
	v_sub_f32_e32 v137, v137, v177
	v_sub_f32_e32 v136, v136, v177
	v_sub_f32_e32 v135, v135, v177
	v_sub_f32_e32 v134, v134, v177
	v_sub_f32_e32 v133, v133, v177
	v_sub_f32_e32 v132, v132, v177
	v_sub_f32_e32 v131, v131, v177
	v_sub_f32_e32 v130, v130, v177
	v_sub_f32_e32 v129, v129, v177
	v_sub_f32_e32 v128, v128, v177
	v_sub_f32_e32 v127, v127, v177
	v_sub_f32_e32 v126, v126, v177
	v_sub_f32_e32 v125, v125, v177
	v_sub_f32_e32 v124, v124, v177
	v_sub_f32_e32 v123, v123, v177
	v_sub_f32_e32 v122, v122, v177
	v_sub_f32_e32 v121, v121, v177
	v_sub_f32_e32 v120, v120, v177
	v_sub_f32_e32 v119, v119, v177
	v_sub_f32_e32 v118, v118, v177
	v_sub_f32_e32 v117, v117, v177
	v_sub_f32_e32 v116, v116, v177
	v_sub_f32_e32 v115, v115, v177
	v_sub_f32_e32 v114, v114, v177
	v_sub_f32_e32 v113, v113, v177
	v_sub_f32_e32 v112, v112, v177
	v_pk_mul_f32 v[110:111], v[110:111], v[176:177] op_sel_hi:[1,0]
	v_pk_mul_f32 v[108:109], v[108:109], v[176:177] op_sel_hi:[1,0]
	v_pk_mul_f32 v[106:107], v[106:107], v[176:177] op_sel_hi:[1,0]
	v_pk_mul_f32 v[104:105], v[104:105], v[176:177] op_sel_hi:[1,0]
	v_pk_mul_f32 v[102:103], v[102:103], v[176:177] op_sel_hi:[1,0]
	v_pk_mul_f32 v[100:101], v[100:101], v[176:177] op_sel_hi:[1,0]
	v_pk_mul_f32 v[98:99], v[98:99], v[176:177] op_sel_hi:[1,0]
	v_pk_mul_f32 v[96:97], v[96:97], v[176:177] op_sel_hi:[1,0]
	v_pk_mul_f32 v[94:95], v[94:95], v[176:177] op_sel_hi:[1,0]
	v_pk_mul_f32 v[92:93], v[92:93], v[176:177] op_sel_hi:[1,0]
	v_pk_mul_f32 v[90:91], v[90:91], v[176:177] op_sel_hi:[1,0]
	v_pk_mul_f32 v[88:89], v[88:89], v[176:177] op_sel_hi:[1,0]
	v_pk_mul_f32 v[86:87], v[86:87], v[176:177] op_sel_hi:[1,0]
	v_pk_mul_f32 v[84:85], v[84:85], v[176:177] op_sel_hi:[1,0]
	v_pk_mul_f32 v[82:83], v[82:83], v[176:177] op_sel_hi:[1,0]
	v_pk_mul_f32 v[80:81], v[80:81], v[176:177] op_sel_hi:[1,0]
	s_branch .LBB0_1663

.LBB0_1699:
	s_or_b64 exec, exec, s[16:17]
	v_max_f32_e32 v64, v53, v53
	v_max_f32_e32 v66, v0, v0
	v_max_f32_e32 v64, v66, v64
	v_max3_f32 v64, v64, v62, v60
	v_max3_f32 v66, v2, v3, v65
	v_max3_f32 v64, v64, v63, v4
	v_max3_f32 v66, v66, v6, v7
	v_max3_f32 v64, v64, v5, v58
	v_max3_f32 v66, v66, v56, v59
	v_max3_f32 v64, v64, v61, v8
	v_max3_f32 v66, v66, v10, v11
	v_max3_f32 v64, v64, v9, v54
	v_max3_f32 v66, v66, v52, v55
	v_max3_f32 v64, v64, v57, v12
	v_max3_f32 v66, v66, v14, v15
	v_max3_f32 v64, v64, v13, v50
	v_max3_f32 v66, v66, v48, v49
	v_max3_f32 v78, v64, v51, v66
	v_add_u32_e32 v64, s19, v127
	v_add_u32_e32 v64, v64, v128
	ds_read_b64_tr_b16 v[104:105], v64 offset:18432
	ds_read_b64_tr_b16 v[106:107], v64 offset:19584
	ds_read_b64_tr_b16 v[76:77], v64 offset:19648
	ds_read_b64_tr_b16 v[74:75], v64 offset:18496
	ds_read_b64_tr_b16 v[70:71], v64 offset:20736
	ds_read_b64_tr_b16 v[72:73], v64 offset:21888
	ds_read_b64_tr_b16 v[68:69], v64 offset:21952
	ds_read_b64_tr_b16 v[66:67], v64 offset:20800
	v_mov_b32_e32 v79, v78
	s_nop 1
	v_permlane32_swap_b32_e32 v79, v78
	s_waitcnt lgkmcnt(0)
	v_max_f32_e32 v78, v78, v79
	v_cmp_lt_f32_e32 vcc, s28, v78
	s_cbranch_vccz .LBB0_1701
	v_max_f32_e32 v78, v78, v78
	v_max_f32_e32 v79, 0, v78
	v_exp_f32_e64 v78, -v79
	v_add_f32_e32 v115, v115, v79
	v_sub_f32_e32 v15, v15, v79
	v_sub_f32_e32 v14, v14, v79
	v_mul_f32_e32 v129, v129, v78
	v_pk_mul_f32 v[46:47], v[46:47], v[78:79] op_sel_hi:[1,0]
	v_pk_mul_f32 v[44:45], v[44:45], v[78:79] op_sel_hi:[1,0]
	v_pk_mul_f32 v[42:43], v[42:43], v[78:79] op_sel_hi:[1,0]
	v_pk_mul_f32 v[40:41], v[40:41], v[78:79] op_sel_hi:[1,0]
	v_pk_mul_f32 v[38:39], v[38:39], v[78:79] op_sel_hi:[1,0]
	v_pk_mul_f32 v[36:37], v[36:37], v[78:79] op_sel_hi:[1,0]
	v_pk_mul_f32 v[34:35], v[34:35], v[78:79] op_sel_hi:[1,0]
	v_pk_mul_f32 v[32:33], v[32:33], v[78:79] op_sel_hi:[1,0]
	v_pk_mul_f32 v[30:31], v[30:31], v[78:79] op_sel_hi:[1,0]
	v_pk_mul_f32 v[28:29], v[28:29], v[78:79] op_sel_hi:[1,0]
	v_pk_mul_f32 v[26:27], v[26:27], v[78:79] op_sel_hi:[1,0]
	v_pk_mul_f32 v[24:25], v[24:25], v[78:79] op_sel_hi:[1,0]
	v_pk_mul_f32 v[22:23], v[22:23], v[78:79] op_sel_hi:[1,0]
	v_pk_mul_f32 v[20:21], v[20:21], v[78:79] op_sel_hi:[1,0]
	v_pk_mul_f32 v[18:19], v[18:19], v[78:79] op_sel_hi:[1,0]
	v_pk_mul_f32 v[16:17], v[16:17], v[78:79] op_sel_hi:[1,0]
	v_sub_f32_e32 v13, v13, v79
	v_sub_f32_e32 v12, v12, v79
	v_sub_f32_e32 v11, v11, v79
	v_sub_f32_e32 v10, v10, v79
	v_sub_f32_e32 v9, v9, v79
	v_sub_f32_e32 v8, v8, v79
	v_sub_f32_e32 v7, v7, v79
	v_sub_f32_e32 v6, v6, v79
	v_sub_f32_e32 v5, v5, v79
	v_sub_f32_e32 v4, v4, v79
	v_sub_f32_e32 v3, v3, v79
	v_sub_f32_e32 v2, v2, v79
	v_sub_f32_e32 v53, v53, v79
	v_sub_f32_e32 v0, v0, v79
	v_sub_f32_e32 v49, v49, v79
	v_sub_f32_e32 v48, v48, v79
	v_sub_f32_e32 v51, v51, v79
	v_sub_f32_e32 v50, v50, v79
	v_sub_f32_e32 v55, v55, v79
	v_sub_f32_e32 v52, v52, v79
	v_sub_f32_e32 v57, v57, v79
	v_sub_f32_e32 v54, v54, v79
	v_sub_f32_e32 v59, v59, v79
	v_sub_f32_e32 v56, v56, v79
	v_sub_f32_e32 v61, v61, v79
	v_sub_f32_e32 v58, v58, v79
	v_sub_f32_e32 v63, v63, v79
	v_sub_f32_e32 v60, v60, v79
	v_sub_f32_e32 v65, v65, v79
	v_sub_f32_e32 v62, v62, v79

.LBB0_1745:
	s_or_b64 exec, exec, s[0:1]
	v_exp_f32_e32 v168, v118
	v_exp_f32_e32 v118, v102
	v_exp_f32_e32 v169, v119
	v_exp_f32_e32 v119, v103
	v_exp_f32_e32 v170, v120
	v_exp_f32_e32 v120, v104
	v_exp_f32_e32 v171, v121
	v_exp_f32_e32 v121, v105
	v_exp_f32_e32 v122, v122
	v_exp_f32_e32 v102, v106
	v_exp_f32_e32 v123, v123
	v_exp_f32_e32 v124, v124
	v_exp_f32_e32 v104, v108
	v_exp_f32_e32 v125, v125
	v_exp_f32_e32 v105, v109
	v_exp_f32_e32 v103, v107
	v_exp_f32_e32 v164, v114
	v_exp_f32_e32 v114, v98
	v_exp_f32_e32 v165, v115
	v_exp_f32_e32 v115, v99
	v_exp_f32_e32 v166, v116
	v_exp_f32_e32 v116, v100
	v_exp_f32_e32 v167, v117
	v_exp_f32_e32 v117, v101
	v_exp_f32_e32 v162, v126
	v_exp_f32_e32 v98, v110
	v_exp_f32_e32 v163, v127
	v_exp_f32_e32 v126, v128
	v_exp_f32_e32 v100, v112
	v_exp_f32_e32 v127, v129
	v_exp_f32_e32 v101, v113
	v_exp_f32_e32 v99, v111
	v_pk_add_f32 v[108:109], v[104:105], v[124:125]
	v_pk_add_f32 v[112:113], v[102:103], v[122:123]
	v_pk_add_f32 v[110:111], v[100:101], v[126:127]
	v_pk_add_f32 v[106:107], v[98:99], v[162:163]
	v_pk_add_f32 v[128:129], v[120:121], v[170:171]
	v_pk_add_f32 v[176:177], v[118:119], v[168:169]
	v_pk_add_f32 v[178:179], v[116:117], v[166:167]
	v_pk_add_f32 v[180:181], v[114:115], v[164:165]
	v_add_f32_e32 v112, v112, v113
	v_add_f32_e32 v108, v108, v109
	v_add_f32_e32 v180, v180, v181
	v_add_f32_e32 v178, v178, v179
	v_add_f32_e32 v176, v176, v177
	v_add_f32_e32 v128, v128, v129
	v_add_f32_e32 v129, v112, v108
	v_add_f32_e32 v112, v106, v107
	v_add3_u32 v179, s15, v187, v188
	v_add_f32_e32 v110, v110, v111
	v_add_f32_e32 v178, v180, v178
	v_add_f32_e32 v128, v176, v128
	ds_read_b64_tr_b16 v[106:107], v179 offset:18432
	ds_read_b64_tr_b16 v[108:109], v179 offset:19584
	v_add_f32_e32 v176, v112, v110
	v_cvt_pk_bf16_f32 v110, v164, v165
	v_cvt_pk_bf16_f32 v111, v166, v167
	ds_read_b64_tr_b16 v[166:167], v179 offset:19648
	ds_read_b64_tr_b16 v[164:165], v179 offset:18496
	v_cvt_pk_bf16_f32 v112, v168, v169
	v_cvt_pk_bf16_f32 v113, v170, v171
	v_add_f32_e32 v178, v178, v128
	v_add_f32_e32 v180, v129, v176
	v_exp_f32_e32 v128, v82
	v_exp_f32_e32 v129, v83
	v_exp_f32_e32 v168, v84
	v_exp_f32_e32 v169, v85
	v_exp_f32_e32 v170, v86
	v_exp_f32_e32 v171, v87
	v_exp_f32_e32 v176, v88
	v_exp_f32_e32 v177, v89
	s_waitcnt lgkmcnt(2)
	v_mfma_f32_32x32x16_bf16 v[18:33], v[106:109], v[110:113], v[18:33]
	v_cvt_pk_bf16_f32 v82, v128, v129
	v_cvt_pk_bf16_f32 v83, v168, v169
	v_cvt_pk_bf16_f32 v84, v170, v171
	v_cvt_pk_bf16_f32 v85, v176, v177
	v_exp_f32_e32 v94, v94
	v_exp_f32_e32 v95, v95
	v_exp_f32_e32 v96, v96
	s_waitcnt lgkmcnt(0)
	v_mfma_f32_32x32x16_bf16 v[2:17], v[164:167], v[110:113], v[2:17]
	v_exp_f32_e32 v97, v97
	v_add_f32_e32 v86, v178, v180
	v_add_f32_e32 v189, v189, v86
	v_cvt_pk_bf16_f32 v86, v122, v123
	v_cvt_pk_bf16_f32 v87, v124, v125
	v_cvt_pk_bf16_f32 v88, v162, v163
	v_cvt_pk_bf16_f32 v89, v126, v127
	v_mfma_f32_32x32x16_bf16 v[34:49], v[106:109], v[82:85], v[34:49]
	ds_read_b64_tr_b16 v[106:107], v179 offset:20736
	ds_read_b64_tr_b16 v[108:109], v179 offset:21888
	ds_read_b64_tr_b16 v[112:113], v179 offset:21952
	ds_read_b64_tr_b16 v[110:111], v179 offset:20800
	v_cvt_pk_bf16_f32 v102, v102, v103
	v_cvt_pk_bf16_f32 v103, v104, v105
	v_cvt_pk_bf16_f32 v104, v98, v99
	v_cvt_pk_bf16_f32 v105, v100, v101
	v_exp_f32_e32 v98, v66
	v_mfma_f32_32x32x16_bf16 v[50:65], v[164:167], v[82:85], v[50:65]
	v_cvt_pk_bf16_f32 v82, v114, v115
	v_cvt_pk_bf16_f32 v83, v116, v117
	v_exp_f32_e32 v114, v90
	v_exp_f32_e32 v115, v91
	v_exp_f32_e32 v116, v92
	v_exp_f32_e32 v117, v93
	v_exp_f32_e32 v99, v67
	s_waitcnt lgkmcnt(2)
	v_mfma_f32_32x32x16_bf16 v[18:33], v[106:109], v[86:89], v[18:33]
	v_exp_f32_e32 v100, v68
	ds_read_b64_tr_b16 v[90:91], v179 offset:23040
	ds_read_b64_tr_b16 v[92:93], v179 offset:24192
	v_exp_f32_e32 v101, v69
	ds_read_b64_tr_b16 v[68:69], v179 offset:24256
	ds_read_b64_tr_b16 v[66:67], v179 offset:23104
	v_exp_f32_e32 v78, v78
	v_exp_f32_e32 v79, v79
	v_cvt_pk_bf16_f32 v84, v118, v119
	s_waitcnt lgkmcnt(4)
	v_mfma_f32_32x32x16_bf16 v[2:17], v[110:113], v[86:89], v[2:17]
	v_cvt_pk_bf16_f32 v86, v114, v115
	v_cvt_pk_bf16_f32 v87, v116, v117
	v_cvt_pk_bf16_f32 v88, v94, v95
	v_cvt_pk_bf16_f32 v89, v96, v97
	v_cvt_pk_bf16_f32 v85, v120, v121
	v_exp_f32_e32 v80, v80
	v_exp_f32_e32 v81, v81
	v_mfma_f32_32x32x16_bf16 v[34:49], v[106:109], v[86:89], v[34:49]
	v_exp_f32_e32 v106, v74
	v_exp_f32_e32 v107, v75
	v_exp_f32_e32 v108, v76
	v_exp_f32_e32 v109, v77
	ds_read_b64_tr_b16 v[74:75], v179 offset:25344
	ds_read_b64_tr_b16 v[76:77], v179 offset:26496
	v_mfma_f32_32x32x16_bf16 v[50:65], v[110:113], v[86:89], v[50:65]
	v_exp_f32_e32 v86, v70
	v_exp_f32_e32 v87, v71
	v_exp_f32_e32 v88, v72
	v_exp_f32_e32 v89, v73
	v_cvt_pk_bf16_f32 v70, v98, v99
	v_cvt_pk_bf16_f32 v71, v100, v101
	v_cvt_pk_bf16_f32 v72, v86, v87
	v_cvt_pk_bf16_f32 v73, v88, v89
	s_waitcnt lgkmcnt(4)
	v_mfma_f32_32x32x16_bf16 v[18:33], v[90:93], v[82:85], v[18:33]
	v_add_f32_e64 v86, v86, v170
	v_add_f32_e64 v87, v87, v171
	s_waitcnt lgkmcnt(2)
	v_mfma_f32_32x32x16_bf16 v[2:17], v[66:69], v[82:85], v[2:17]
	v_add_f32_e64 v82, v88, v176
	v_add_f32_e64 v83, v89, v177
	v_add_f32_e64 v88, v78, v94
	v_add_f32_e64 v89, v79, v95
	v_add_f32_e64 v94, v98, v128
	v_add_f32_e64 v95, v99, v129
	v_pk_add_f32 v[84:85], v[80:81], v[96:97]
	v_mfma_f32_32x32x16_bf16 v[34:49], v[90:93], v[70:73], v[34:49]
	v_add_f32_e64 v90, v100, v168
	v_add_f32_e64 v91, v101, v169
	v_add_f32_e64 v92, v108, v116
	v_add_f32_e64 v93, v109, v117
	v_mfma_f32_32x32x16_bf16 v[50:65], v[66:69], v[70:73], v[50:65]
	v_add_f32_e64 v66, v106, v114
	v_add_f32_e64 v67, v107, v115
	v_add_f32_e32 v70, v94, v95
	v_add_f32_e32 v71, v66, v67
	ds_read_b64_tr_b16 v[68:69], v179 offset:26560
	ds_read_b64_tr_b16 v[66:67], v179 offset:25408
	v_add_f32_e32 v72, v90, v91
	v_add_f32_e32 v73, v92, v93
	s_waitcnt lgkmcnt(2)
	v_mfma_f32_32x32x16_bf16 v[18:33], v[74:77], v[102:105], v[18:33]
	v_add_f32_e64 v90, v70, v72
	v_add_f32_e64 v91, v71, v73
	v_add_f32_e32 v86, v86, v87
	v_add_f32_e32 v87, v88, v89
	v_cvt_pk_bf16_f32 v70, v106, v107
	v_cvt_pk_bf16_f32 v71, v108, v109
	v_cvt_pk_bf16_f32 v72, v78, v79
	v_cvt_pk_bf16_f32 v73, v80, v81
	s_waitcnt lgkmcnt(0)
	v_mfma_f32_32x32x16_bf16 v[2:17], v[66:69], v[102:105], v[2:17]
	v_mfma_f32_32x32x16_bf16 v[34:49], v[74:77], v[70:73], v[34:49]
	v_add_f32_e32 v74, v82, v83
	v_add_f32_e32 v75, v84, v85
	v_add_f32_e64 v74, v86, v74
	v_add_f32_e64 v75, v87, v75
	v_add_f32_e64 v74, v90, v74
	v_add_f32_e64 v75, v91, v75
	v_add_f32_e32 v74, v74, v75
	v_mfma_f32_32x32x16_bf16 v[50:65], v[66:69], v[70:73], v[50:65]
	v_add_f32_e32 v159, v159, v74

.LBB0_1764:
	s_or_b64 exec, exec, s[6:7]
	v_max_f32_e32 v98, v83, v83
	v_max_f32_e32 v99, v82, v82
	v_max_f32_e32 v98, v99, v98
	v_max3_f32 v99, v84, v85, v67
	v_max3_f32 v98, v98, v66, v68
	v_max3_f32 v98, v98, v69, v86
	v_max3_f32 v99, v99, v88, v89
	v_max3_f32 v98, v98, v87, v70
	v_max3_f32 v99, v99, v72, v73
	v_max3_f32 v98, v98, v71, v90
	v_max3_f32 v99, v99, v92, v93
	v_max3_f32 v98, v98, v91, v74
	v_max3_f32 v99, v99, v76, v77
	v_max3_f32 v98, v98, v75, v94
	v_max3_f32 v99, v99, v96, v97
	v_max3_f32 v98, v98, v95, v78
	v_max3_f32 v99, v99, v80, v81
	v_max3_f32 v98, v98, v79, v99
	v_mov_b32_e32 v99, v98
	s_nop 1
	v_permlane32_swap_b32_e32 v99, v98
	s_waitcnt lgkmcnt(0)
	v_max_f32_e32 v98, v98, v99
	v_cmp_lt_f32_e32 vcc, s28, v98
	s_cbranch_vccz .LBB0_1766
	v_max_f32_e32 v98, v98, v98
	v_max_f32_e32 v99, 0, v98
	v_exp_f32_e64 v98, -v99
	v_add_f32_e32 v191, v191, v99
	v_sub_f32_e32 v97, v97, v99
	v_sub_f32_e32 v96, v96, v99
	v_mul_f32_e32 v189, v189, v98
	v_sub_f32_e32 v95, v95, v99
	v_sub_f32_e32 v94, v94, v99
	v_sub_f32_e32 v93, v93, v99
	v_sub_f32_e32 v92, v92, v99
	v_sub_f32_e32 v91, v91, v99
	v_sub_f32_e32 v90, v90, v99
	v_sub_f32_e32 v89, v89, v99
	v_sub_f32_e32 v88, v88, v99
	v_sub_f32_e32 v87, v87, v99
	v_sub_f32_e32 v86, v86, v99
	v_sub_f32_e32 v85, v85, v99
	v_sub_f32_e32 v84, v84, v99
	v_sub_f32_e32 v83, v83, v99
	v_sub_f32_e32 v82, v82, v99
	v_sub_f32_e32 v81, v81, v99
	v_sub_f32_e32 v80, v80, v99
	v_sub_f32_e32 v79, v79, v99
	v_sub_f32_e32 v78, v78, v99
	v_sub_f32_e32 v77, v77, v99
	v_sub_f32_e32 v76, v76, v99
	v_sub_f32_e32 v75, v75, v99
	v_sub_f32_e32 v74, v74, v99
	v_sub_f32_e32 v73, v73, v99
	v_sub_f32_e32 v72, v72, v99
	v_sub_f32_e32 v71, v71, v99
	v_sub_f32_e32 v70, v70, v99
	v_sub_f32_e32 v69, v69, v99
	v_sub_f32_e32 v68, v68, v99
	v_sub_f32_e32 v67, v67, v99
	v_sub_f32_e32 v66, v66, v99
	v_pk_mul_f32 v[48:49], v[48:49], v[98:99] op_sel_hi:[1,0]
	v_pk_mul_f32 v[46:47], v[46:47], v[98:99] op_sel_hi:[1,0]
	v_pk_mul_f32 v[44:45], v[44:45], v[98:99] op_sel_hi:[1,0]
	v_pk_mul_f32 v[42:43], v[42:43], v[98:99] op_sel_hi:[1,0]
	v_pk_mul_f32 v[40:41], v[40:41], v[98:99] op_sel_hi:[1,0]
	v_pk_mul_f32 v[38:39], v[38:39], v[98:99] op_sel_hi:[1,0]
	v_pk_mul_f32 v[36:37], v[36:37], v[98:99] op_sel_hi:[1,0]
	v_pk_mul_f32 v[34:35], v[34:35], v[98:99] op_sel_hi:[1,0]
	v_pk_mul_f32 v[16:17], v[16:17], v[98:99] op_sel_hi:[1,0]
	v_pk_mul_f32 v[14:15], v[14:15], v[98:99] op_sel_hi:[1,0]
	v_pk_mul_f32 v[12:13], v[12:13], v[98:99] op_sel_hi:[1,0]
	v_pk_mul_f32 v[10:11], v[10:11], v[98:99] op_sel_hi:[1,0]
	v_pk_mul_f32 v[8:9], v[8:9], v[98:99] op_sel_hi:[1,0]
	v_pk_mul_f32 v[6:7], v[6:7], v[98:99] op_sel_hi:[1,0]
	v_pk_mul_f32 v[4:5], v[4:5], v[98:99] op_sel_hi:[1,0]
	v_pk_mul_f32 v[2:3], v[2:3], v[98:99] op_sel_hi:[1,0]

.LBB0_1768:
	s_or_b64 exec, exec, s[6:7]
	s_nop 5
	v_max_f32_e32 v162, v115, v115
	v_max_f32_e32 v163, v114, v114
	v_max_f32_e32 v162, v163, v162
	v_max3_f32 v163, v116, v117, v99
	v_max3_f32 v162, v162, v98, v100
	v_max3_f32 v162, v162, v101, v118
	v_max3_f32 v163, v163, v120, v121
	v_max3_f32 v162, v162, v119, v102
	v_max3_f32 v163, v163, v104, v105
	v_max3_f32 v162, v162, v103, v122
	v_max3_f32 v163, v163, v124, v125
	v_max3_f32 v162, v162, v123, v106
	v_max3_f32 v163, v163, v108, v109
	v_max3_f32 v162, v162, v107, v126
	v_max3_f32 v163, v163, v128, v129
	v_max3_f32 v162, v162, v127, v110
	v_max3_f32 v163, v163, v112, v113
	v_max3_f32 v162, v162, v111, v163
	v_mov_b32_e32 v163, v162
	s_nop 1
	v_permlane32_swap_b32_e32 v163, v162
	s_waitcnt lgkmcnt(0)
	v_max_f32_e32 v162, v162, v163
	v_cmp_lt_f32_e32 vcc, s28, v162
	s_cbranch_vccz .LBB0_1757
	v_max_f32_e32 v162, v162, v162
	v_max_f32_e32 v163, 0, v162
	v_exp_f32_e64 v162, -v163
	v_add_f32_e32 v190, v190, v163
	v_sub_f32_e32 v129, v129, v163
	v_sub_f32_e32 v128, v128, v163
	v_mul_f32_e32 v159, v159, v162
	v_sub_f32_e32 v127, v127, v163
	v_sub_f32_e32 v126, v126, v163
	v_sub_f32_e32 v125, v125, v163
	v_sub_f32_e32 v124, v124, v163
	v_sub_f32_e32 v123, v123, v163
	v_sub_f32_e32 v122, v122, v163
	v_sub_f32_e32 v121, v121, v163
	v_sub_f32_e32 v120, v120, v163
	v_sub_f32_e32 v119, v119, v163
	v_sub_f32_e32 v118, v118, v163
	v_sub_f32_e32 v117, v117, v163
	v_sub_f32_e32 v116, v116, v163
	v_sub_f32_e32 v115, v115, v163
	v_sub_f32_e32 v114, v114, v163
	v_sub_f32_e32 v113, v113, v163
	v_sub_f32_e32 v112, v112, v163
	v_sub_f32_e32 v111, v111, v163
	v_sub_f32_e32 v110, v110, v163
	v_sub_f32_e32 v109, v109, v163
	v_sub_f32_e32 v108, v108, v163
	v_sub_f32_e32 v107, v107, v163
	v_sub_f32_e32 v106, v106, v163
	v_sub_f32_e32 v105, v105, v163
	v_sub_f32_e32 v104, v104, v163
	v_sub_f32_e32 v103, v103, v163
	v_sub_f32_e32 v102, v102, v163
	v_sub_f32_e32 v101, v101, v163
	v_sub_f32_e32 v100, v100, v163
	v_sub_f32_e32 v99, v99, v163
	v_sub_f32_e32 v98, v98, v163
	v_pk_mul_f32 v[32:33], v[32:33], v[162:163] op_sel_hi:[1,0]
	v_pk_mul_f32 v[30:31], v[30:31], v[162:163] op_sel_hi:[1,0]
	v_pk_mul_f32 v[28:29], v[28:29], v[162:163] op_sel_hi:[1,0]
	v_pk_mul_f32 v[26:27], v[26:27], v[162:163] op_sel_hi:[1,0]
	v_pk_mul_f32 v[24:25], v[24:25], v[162:163] op_sel_hi:[1,0]
	v_pk_mul_f32 v[22:23], v[22:23], v[162:163] op_sel_hi:[1,0]
	v_pk_mul_f32 v[20:21], v[20:21], v[162:163] op_sel_hi:[1,0]
	v_pk_mul_f32 v[18:19], v[18:19], v[162:163] op_sel_hi:[1,0]
	v_pk_mul_f32 v[64:65], v[64:65], v[162:163] op_sel_hi:[1,0]
	v_pk_mul_f32 v[62:63], v[62:63], v[162:163] op_sel_hi:[1,0]
	v_pk_mul_f32 v[60:61], v[60:61], v[162:163] op_sel_hi:[1,0]
	v_pk_mul_f32 v[58:59], v[58:59], v[162:163] op_sel_hi:[1,0]
	v_pk_mul_f32 v[56:57], v[56:57], v[162:163] op_sel_hi:[1,0]
	v_pk_mul_f32 v[54:55], v[54:55], v[162:163] op_sel_hi:[1,0]
	v_pk_mul_f32 v[52:53], v[52:53], v[162:163] op_sel_hi:[1,0]
	v_pk_mul_f32 v[50:51], v[50:51], v[162:163] op_sel_hi:[1,0]
	s_branch .LBB0_1757
